# slot loop: odd XCDs run in-proj before PEER retrieval, even XCDs the opposite order (both workgroups of a CU always agree)
# speedup vs baseline: 1.0803x; 1.0002x over previous
; #define LND asm volatile("" : "+s"(l), "+s"(pass))
; __global__ void __launch_bounds__(256, 2) fwd_megakernel(Params P) {
;     ...
;     const int role = ROLE_SPLIT ? ((blockIdx.x >> 8) & 1) : ROLE_ALL;
; #pragma unroll 1
;     for (int it = 0; it < 3; ++it) {
; #pragma unroll 1
;       for (int step = 0; step < 2; ++step) {
;         int pass;
;         if ((step ^ role) == 0) {
;           if (it < 2) { pass = __builtin_amdgcn_readfirstlane(it); LND; phase_inproj(P, l, pass, smem); }
;         } else {
;           if (it > 0) { pass = __builtin_amdgcn_readfirstlane(it - 1); LND; phase11(P, l, pass, smem); }
;         }
;       }
.LBB0_123:
	s_cmp_lg_u32 s51, 0
	s_cselect_b64 s[26:27], -1, 0
	s_cmp_eq_u32 s51, 2
	s_cselect_b64 s[4:5], -1, 0
	v_writelane_b32 v252, s4, 34
	s_cmp_lg_u32 s51, 2
	s_cselect_b64 s[6:7], -1, 0
	v_writelane_b32 v252, s5, 35
	v_writelane_b32 v252, s51, 36
	s_mov_b64 s[72:73], -1
	s_mov_b32 s2, s0
	v_writelane_b32 v252, s6, 37
	s_nop 1
	v_writelane_b32 v252, s7, 38
	s_mov_b64 s[40:41], -1
	s_getreg_b32 vcc_lo, hwreg(HW_REG_XCC_ID, 0, 4)
	s_nop 1
	s_bitcmp1_b32 vcc_lo, 0
	s_cbranch_scc1 .LBB0_277
	s_branch .LBB0_125
.Lsplit_latch:
	s_getreg_b32 vcc_lo, hwreg(HW_REG_XCC_ID, 0, 4)
	s_nop 1
	s_bitcmp1_b32 vcc_lo, 0
	s_cbranch_scc0 .LBB0_124
	s_waitcnt vmcnt(0) lgkmcnt(0)
	s_barrier
	v_readlane_b32 s51, v252, 36
	s_mov_b32 s2, s0
	s_nop 1
	s_cmp_lg_u32 s51, 0
	s_cselect_b64 s[26:27], -1, 0
	s_branch .LBB0_125
